# phase H tile start: row-scale loads issued first (all threads, rows tid&255), sum/rsqrt/LDS write moved to the GEMM prologue's existing full wait
# speedup vs baseline: 1.0026x; 1.0026x over previous
; #define WAIT_V(n) asm volatile("s_waitcnt vmcnt(" #n ")" ::: "memory")
; #define BAR __builtin_amdgcn_s_barrier()
; DI void gemm256(int wv0, f32x4 (&acc)[2][2][4][2], const u16* __restrict__ A, int lda, const u16* __restrict__ Bt, int ldb,
;                 int K, unsigned char* smem) {
;     ...
;   int sr0, sc0, sr1, sc1;
;   stage_rc(tid * 16, sr0, sc0);
;   stage_rc(tid * 16 + 8192, sr1, sc1);
;   const u16* a0 = A + (size_t)sr0 * lda + sc0;
;   const u16* a1 = A + (size_t)sr1 * lda + sc1;
;   const u16* b0 = Bt + (size_t)sr0 * ldb + sc0;
;   const u16* b1 = Bt + (size_t)sr1 * ldb + sc1;
;     ...
; #pragma unroll
;   for (int a = 0; a < 2; ++a)
; #pragma unroll
;     for (int b = 0; b < 2; ++b)
; #pragma unroll
;       for (int m = 0; m < 4; ++m)
; #pragma unroll
;         for (int n = 0; n < 2; ++n) acc[a][b][m][n] = f32x4{0.f, 0.f, 0.f, 0.f};
;   bf16x8 At[4][2], B0[2][2], B1[2][2];
;   const int nt = K / 64;
;   WAIT_V(0);
;   __syncthreads();
;   STAGE_B(SB(0, 0), 0, 0) STAGE_A(SA(0, 0), 0, 0)
;   STAGE_B(SB(0, 1), 1, 0) STAGE_A(SA(0, 1), 1, 0)
;   if (wr == 1) BAR;
;   WAIT_V(4); BAR;
;   STAGE_B(SB(1, 0), 0, 1) STAGE_A(SA(1, 0), 0, 1) STAGE_B(SB(1, 1), 1, 1)
; DI void phaseH(int wv0, PP p, unsigned char* smem) {
;     ...
;   for (int id = blockIdx.x; id < 128 * 16; id += gridDim.x) {
;     int pm, pn;
;     tile_map_n16(id, pm, pn);
;     const int brow = pm * 256, bcol = pn * 256;
;     const int tid = my_tid(wv0);
;     if (tid < 256) {
;       const float4* s = (const float4*)(SS1 + (size_t)(brow + tid) * 16);
;       const float4 a = s[0], b = s[1], c = s[2], d = s[3];
;       const float t = a.x + a.y + a.z + a.w + b.x + b.y + b.z + b.w + c.x + c.y + c.z + c.w + d.x + d.y + d.z + d.w;
;       sR[tid] = rsqrtf(t * (1.f / 1024.f) + 1e-6f);
;     }
.LBB0_1134:
	s_ashr_i32 s4, s67, 4
	s_and_b32 s68, s4, -16
	s_lshl_b32 s4, s67, 1
	s_and_b32 s69, s4, 12
	s_or_b32 s4, s68, s69
	s_bfe_u32 s70, s67, 0x20006
	s_or_b32 s4, s4, s70
	s_lshl_b32 s46, s4, 8
	s_nop 0
	v_and_b32_e32 v0, 0xff, v142
	v_add_u32_e32 v2, s46, v0
	v_ashrrev_i32_e32 v3, 31, v2
	v_lshlrev_b64 v[2:3], 6, v[2:3]
	v_lshl_add_u64 v[14:15], s[8:9], 0, v[2:3]
	global_load_dwordx4 v[168:171], v[14:15], off
	global_load_dwordx4 v[172:175], v[14:15], off offset:16
	global_load_dwordx4 v[176:179], v[14:15], off offset:32
	global_load_dwordx4 v[180:183], v[14:15], off offset:48
.LBB0_1136:
	v_mov_b32_e32 v12, v142
	s_lshl_b32 s4, s67, 3
	v_bfe_i32 v1, v12, 27, 1
	v_lshlrev_b32_e32 v13, 4, v12
	v_lshrrev_b32_e32 v1, 22, v1
	v_add_u32_e32 v1, v13, v1
	v_and_b32_e32 v1, 0xfffffc00, v1
	v_ashrrev_i32_e32 v0, 31, v12
	v_sub_u32_e32 v1, v13, v1
	v_lshrrev_b32_e32 v0, 26, v0
	v_lshrrev_b32_e32 v2, 4, v1
	v_add_u32_e32 v0, v12, v0
	v_bitop3_b32 v2, v2, v1, 32 bitop3:0x6c
	v_ashrrev_i32_e32 v1, 31, v1
	v_ashrrev_i32_e32 v0, 6, v0
	v_lshrrev_b32_e32 v1, 26, v1
	v_lshlrev_b32_e32 v3, 3, v0
	v_add_u32_e32 v1, v2, v1
	v_and_b32_e32 v3, -16, v3
	v_ashrrev_i32_e32 v1, 6, v1
	v_add_u32_e32 v4, v1, v3
	v_mul_i32_i24_e32 v1, 64, v1
	v_lshlrev_b32_e32 v0, 5, v0
	v_sub_u32_e32 v1, v2, v1
	v_and_b32_e32 v0, 32, v0
	v_ashrrev_i16_sdwa v1, v144, sext(v1) dst_sel:DWORD dst_unused:UNUSED_PAD src0_sel:DWORD src1_sel:BYTE_0
	v_add_u32_sdwa v0, v0, sext(v1) dst_sel:DWORD dst_unused:UNUSED_PAD src0_sel:DWORD src1_sel:WORD_0
	v_add_u32_e32 v1, 0x2000, v13
	v_ashrrev_i32_e32 v2, 31, v1
	v_lshrrev_b32_e32 v2, 22, v2
	v_add_u32_e32 v2, v1, v2
	v_ashrrev_i32_e32 v2, 10, v2
	v_mul_i32_i24_e32 v3, 0x400, v2
	v_sub_u32_e32 v1, v1, v3
	v_lshrrev_b32_e32 v3, 4, v1
	v_bitop3_b32 v1, v3, v1, 32 bitop3:0x6c
	s_and_b32 s47, s4, 8
	s_bfe_u32 s4, s67, 0x30003
	v_ashrrev_i32_e32 v5, 31, v1
	s_or_b32 s48, s47, s4
	s_ashr_i32 s47, s46, 31
	v_lshrrev_b32_e32 v5, 26, v5
	s_lshl_b64 s[72:73], s[46:47], 11
	v_lshlrev_b32_e32 v3, 3, v2
	v_add_u32_e32 v5, v1, v5
	s_add_u32 s72, s0, s72
	v_and_b32_e32 v3, -16, v3
	v_ashrrev_i32_e32 v6, 6, v5
	s_addc_u32 s73, s1, s73
	s_lshl_b32 s47, s48, 19
	v_add_u32_e32 v8, v6, v3
	v_and_b32_e32 v3, 0xc0, v5
	s_add_u32 s74, s33, s47
	v_lshlrev_b32_e32 v2, 5, v2
	v_sub_u32_e32 v1, v1, v3
	s_addc_u32 s75, s50, 0
	v_and_b32_e32 v2, 32, v2
	v_ashrrev_i16_sdwa v1, v144, sext(v1) dst_sel:DWORD dst_unused:UNUSED_PAD src0_sel:DWORD src1_sel:BYTE_0
	v_ashrrev_i32_e32 v5, 31, v4
	s_add_i32 s47, 32, 0x10000
	v_add_u32_sdwa v2, v2, sext(v1) dst_sel:DWORD dst_unused:UNUSED_PAD src0_sel:DWORD src1_sel:WORD_0
	v_ashrrev_i32_e32 v1, 31, v0
	v_ashrrev_i32_e32 v9, 31, v8
	v_lshlrev_b64 v[6:7], 11, v[4:5]
	v_add_u32_e32 v148, s47, v13
	v_ashrrev_i32_e32 v3, 31, v2
	v_lshl_add_u64 v[10:11], s[74:75], 0, v[6:7]
	v_lshlrev_b64 v[4:5], 11, v[8:9]
	v_lshlrev_b64 v[16:17], 1, v[0:1]
	v_readfirstlane_b32 s47, v148
	v_add_u32_e32 v149, 0x2000, v148
	v_lshl_add_u64 v[8:9], s[74:75], 0, v[4:5]
	v_lshlrev_b64 v[18:19], 1, v[2:3]
	v_lshl_add_u64 v[10:11], v[10:11], 0, v[16:17]
	s_mov_b32 m0, s47
	v_readfirstlane_b32 s47, v149
	v_add_u32_e32 v150, 32, v13
	v_lshl_add_u64 v[14:15], s[72:73], 0, v[6:7]
	v_lshl_add_u64 v[8:9], v[8:9], 0, v[18:19]
	s_waitcnt vmcnt(0)
	s_waitcnt vmcnt(0) lgkmcnt(0)
	v_and_b32_e32 v184, 0xff, v142
	v_lshl_add_u32 v184, v184, 2, 32
	v_add_u32_e32 v184, 0x213e0, v184
	v_add_f32_e32 v185, v168, v169
	v_add_f32_e32 v185, v185, v170
	v_add_f32_e32 v185, v185, v171
	v_add_f32_e32 v185, v185, v172
	v_add_f32_e32 v185, v185, v173
	v_add_f32_e32 v185, v185, v174
	v_add_f32_e32 v185, v185, v175
	v_add_f32_e32 v185, v185, v176
	v_add_f32_e32 v185, v185, v177
	v_add_f32_e32 v185, v185, v178
	v_add_f32_e32 v185, v185, v179
	v_add_f32_e32 v185, v185, v180
	v_add_f32_e32 v185, v185, v181
	v_add_f32_e32 v185, v185, v182
	v_add_f32_e32 v185, v185, v183
	v_fmamk_f32 v185, v185, 0x3a800000, v143
	v_mul_f32_e32 v186, 0x4b800000, v185
	v_cmp_gt_f32_e32 vcc, s66, v185
	s_nop 1
	v_cndmask_b32_e32 v185, v185, v186, vcc
	v_rsq_f32_e32 v185, v185
	s_nop 0
	v_mul_f32_e32 v186, 0x45800000, v185
	v_cndmask_b32_e32 v185, v185, v186, vcc
	ds_write_b32 v184, v185
	s_barrier
	global_load_lds_dwordx4 v[10:11], off
	s_mov_b32 m0, s47
	v_readfirstlane_b32 s47, v150
	v_add_u32_e32 v151, 0x2000, v150
	v_lshl_add_u64 v[132:133], v[14:15], 0, v[16:17]
	global_load_lds_dwordx4 v[8:9], off
	s_mov_b32 m0, s47
	v_readfirstlane_b32 s47, v151
	global_load_lds_dwordx4 v[132:133], off
	s_mov_b32 m0, s47
	s_add_i32 s47, 32, 0x14000
	v_lshl_add_u64 v[14:15], s[72:73], 0, v[4:5]
	v_add_u32_e32 v152, s47, v13
	v_lshl_add_u64 v[130:131], v[14:15], 0, v[18:19]
	v_readfirstlane_b32 s47, v152
	v_add_u32_e32 v153, 0x2000, v152
	global_load_lds_dwordx4 v[130:131], off
	v_lshl_add_u64 v[14:15], v[10:11], 0, s[18:19]
	s_mov_b32 m0, s47
	v_readfirstlane_b32 s47, v153
	v_add_u32_e32 v154, 0x4000, v150
	global_load_lds_dwordx4 v[14:15], off
	v_lshl_add_u64 v[14:15], v[8:9], 0, s[18:19]
	s_mov_b32 m0, s47
	v_readfirstlane_b32 s47, v154
	v_add_u32_e32 v155, 0x6000, v150
	global_load_lds_dwordx4 v[14:15], off
	v_lshl_add_u64 v[14:15], v[132:133], 0, s[18:19]
	s_mov_b32 m0, s47
	v_readfirstlane_b32 s47, v155
	global_load_lds_dwordx4 v[14:15], off
	v_lshl_add_u64 v[14:15], v[130:131], 0, s[18:19]
	s_mov_b32 m0, s47
	s_andn2_b64 vcc, exec, s[12:13]
	global_load_lds_dwordx4 v[14:15], off
	s_cbranch_vccnz .LBB0_1138
	s_barrier
